# v33 + MLA loop: 8 packed v_pk_fma_f32 split into scalar v_fma_f32 pairs
# speedup vs baseline: 1.0039x; 1.0038x over previous
.LBB0_553:
	v_cndmask_b32_e64 v202, v202, v165, s[4:5]
	v_mul_f32_e32 v146, 0xbdd53b94, v202
	v_fmamk_f32 v82, v82, 0x3dd53b94, v146
	v_fmamk_f32 v83, v83, 0x3dd53b94, v146
	v_fmamk_f32 v84, v84, 0x3dd53b94, v146
	v_fmamk_f32 v85, v85, 0x3dd53b94, v146
	v_fmamk_f32 v86, v86, 0x3dd53b94, v146
	v_fmamk_f32 v87, v87, 0x3dd53b94, v146
	v_fmamk_f32 v88, v88, 0x3dd53b94, v146
	v_fmamk_f32 v89, v89, 0x3dd53b94, v146
	v_fmamk_f32 v90, v90, 0x3dd53b94, v146
	v_fmamk_f32 v91, v91, 0x3dd53b94, v146
	v_fmamk_f32 v92, v92, 0x3dd53b94, v146
	v_fmamk_f32 v93, v93, 0x3dd53b94, v146
	v_fmamk_f32 v94, v94, 0x3dd53b94, v146
	v_fmamk_f32 v95, v95, 0x3dd53b94, v146
	v_fmamk_f32 v96, v96, 0x3dd53b94, v146
	v_fmamk_f32 v97, v97, 0x3dd53b94, v146
	s_add_u32 s88, s88, 0xf0000
	v_exp_f32_e32 v229, v82
	v_exp_f32_e32 v231, v83
	v_exp_f32_e32 v227, v84
	v_exp_f32_e32 v230, v85
	v_exp_f32_e32 v226, v86
	v_exp_f32_e32 v228, v87
	v_exp_f32_e32 v224, v88
	v_exp_f32_e32 v225, v89
	v_exp_f32_e32 v221, v90
	v_exp_f32_e32 v223, v91
	v_exp_f32_e32 v220, v92
	v_exp_f32_e32 v222, v93
	v_exp_f32_e32 v217, v94
	v_exp_f32_e32 v219, v95
	v_exp_f32_e32 v216, v96
	v_exp_f32_e32 v218, v97
	s_addc_u32 s87, s87, 0
	v_add_f32_e32 v82, v162, v163
	s_waitcnt vmcnt(0)
	s_add_u32 s20, s20, 0x80000
	v_fmac_f32_e32 v82, v201, v171
	v_add_f32_e32 v171, v232, v233
	s_addc_u32 s21, s21, 0
	s_add_i32 s19, s19, 2
	v_fmac_f32_e32 v171, v82, v164
	v_fma_f32 v164, v66, s34, v146
	v_fma_f32 v165, v67, s34, v146
	v_fma_f32 v162, v68, s34, v146
	v_fma_f32 v163, v69, s34, v146
	v_fma_f32 v156, v70, s34, v146
	v_fma_f32 v157, v71, s34, v146
	v_fma_f32 v154, v72, s34, v146
	v_fma_f32 v155, v73, s34, v146
	v_fma_f32 v152, v74, s34, v146
	v_fma_f32 v153, v75, s34, v146
	v_fma_f32 v150, v76, s34, v146
	v_fma_f32 v151, v77, s34, v146
	v_fma_f32 v148, v78, s34, v146
	v_fma_f32 v149, v79, s34, v146
	v_fma_f32 v147, v81, s34, v146
	v_fma_f32 v146, v80, s34, v146
	s_cmp_ge_u32 s19, s86
	s_mov_b32 s0, s22
	s_mov_b32 s22, s23
	v_mov_b32_e32 v201, v215
	s_waitcnt vmcnt(0)
	s_barrier
	s_cbranch_scc0 .LBB0_543
